# next unit's scoring operands (K tiles 0-1, q_idx rows, head weights) prefetched before the unit boundary; next ticket published at the exchange barrier
# speedup vs baseline: 1.0111x; 1.0007x over previous
.LBB0_405:
	s_or_b64 exec, exec, s[0:1]
	s_add_i32 s86, 0, 0x27090
	s_cmp_lg_u32 s86, -1
	s_cselect_b32 s0, s86, 0
	s_cselect_b32 s1, s5, 0
	v_mov_b32_e32 v2, s0
	v_mov_b32_e32 v3, s1
	s_waitcnt lgkmcnt(0)
	s_barrier
	flat_load_dword v1, v[2:3] sc0 sc1
	s_waitcnt vmcnt(0) lgkmcnt(0)
	v_readfirstlane_b32 s36, v1
	s_cmpk_gt_i32 s36, 0x803
	s_cbranch_scc1 .LBB0_799
	s_add_u32 s50, s18, 0x6300000
	s_addc_u32 s51, s19, 0
	s_add_u32 s0, s18, 0xe700000
	s_addc_u32 s1, s19, 0
	v_writelane_b32 v250, s0, 44
	v_ashrrev_i32_e32 v1, 6, v0
	v_and_b32_e32 v185, 3, v1
	v_writelane_b32 v250, s1, 45
	s_add_u32 s0, s18, 0xeb20000
	s_addc_u32 s1, s19, 0
	v_writelane_b32 v250, s0, 46
	v_lshlrev_b32_e32 v2, 10, v185
	v_and_b32_e32 v184, 63, v0
	v_writelane_b32 v250, s1, 47
	s_add_u32 s0, s18, 0x10d28000
	s_addc_u32 s1, s19, 0
	v_writelane_b32 v250, s0, 48
	v_lshlrev_b32_e32 v3, 3, v0
	v_and_b32_e32 v192, 0xffffffc0, v0
	v_writelane_b32 v250, s1, 49
	s_add_u32 s0, s18, 0x14f28000
	s_addc_u32 s1, s19, 0
	v_writelane_b32 v250, s0, 50
	s_add_i32 s17, 0, 0x23000
	v_lshlrev_b32_e32 v190, 3, v1
	v_writelane_b32 v250, s1, 51
	v_cmp_gt_u32_e64 s[0:1], 64, v0
	v_lshl_add_u32 v191, v1, 12, s17
	v_and_b32_e32 v3, 0xfffff800, v3
	v_writelane_b32 v250, s0, 36
	v_lshl_add_u32 v187, v185, 12, s17
	v_readlane_b32 s6, v251, 52
	v_writelane_b32 v250, s1, 37
	s_movk_i32 s1, 0x100
	v_readlane_b32 s0, v250, 20
	v_cmp_gt_u32_e64 s[40:41], s1, v0
	v_and_b32_e32 v0, 0xffffff00, v0
	v_add_u32_e32 v186, s0, v2
	s_mov_b32 s0, 0x8400
	v_mad_u32_u24 v189, v185, s0, 0
	s_movk_i32 s0, 0x4400
	v_mul_lo_u32 v1, v1, s0
	v_cmp_eq_u32_e64 s[0:1], s1, v0
	v_add_u32_e32 v193, 0, v1
	v_readlane_b32 s10, v251, 55
	v_writelane_b32 v250, s0, 52
	v_readlane_b32 s12, v251, 57
	v_add_u32_e32 v188, v187, v3
	v_writelane_b32 v250, s1, 53
	s_add_u32 s0, s18, 0x6300004
	v_writelane_b32 v250, s0, 54
	s_addc_u32 s0, s19, 0
	v_writelane_b32 v250, s0, 55
	s_add_u32 s0, s18, 0x6300008
	v_writelane_b32 v250, s0, 56
	s_addc_u32 s0, s19, 0
	v_writelane_b32 v250, s0, 57
	s_add_u32 s0, s18, 0x630000c
	v_writelane_b32 v250, s0, 58
	s_addc_u32 s0, s19, 0
	v_writelane_b32 v250, s0, 59
	v_add_u32_e32 v194, 0x11000, v193
	v_readlane_b32 s0, v250, 21
	v_readlane_b32 s7, v251, 53
	v_readlane_b32 s4, v251, 54
	v_add_u32_e32 v195, s0, v2
	v_readlane_b32 s11, v251, 56
	v_readlane_b32 s13, v251, 58
	v_readlane_b32 s14, v250, 2
	v_readlane_b32 s98, v250, 46
	v_readlane_b32 s99, v250, 47
	v_and_b32_e32 v222, 63, v171
	v_lshrrev_b32_e32 v223, 6, v171
	v_lshlrev_b32_e32 v222, 4, v222
	v_lshl_add_u32 v222, v223, 12, v222
	s_nop 1
	global_load_dwordx4 v[80:83], v222, s[98:99]
	global_load_dwordx4 v[84:87], v222, s[98:99] offset:1024
	global_load_dwordx4 v[88:91], v222, s[98:99] offset:2048
	global_load_dwordx4 v[92:95], v222, s[98:99] offset:3072
	s_add_u32 s98, s98, 0x8000
	s_addc_u32 s99, s99, 0
	global_load_dwordx4 v[206:209], v222, s[98:99]
	global_load_dwordx4 v[210:213], v222, s[98:99] offset:1024
	global_load_dwordx4 v[214:217], v222, s[98:99] offset:2048
	global_load_dwordx4 v[218:221], v222, s[98:99] offset:3072
	s_mov_b32 s98, s36
	s_cmpk_lt_i32 s98, 0x804
	s_cbranch_scc0 .Lkq_skip_a
	s_lshl_b32 s98, s98, 2
	s_sub_i32 s98, 0x200c, s98
	v_and_b32_e32 v222, 3, v184
	v_or_b32_e32 v222, s98, v222
	v_lshlrev_b32_e32 v222, 14, v222
	v_lshlrev_b32_e32 v223, 5, v184
	v_and_b32_e32 v223, 0x380, v223
	v_add_u32_e32 v222, v222, v223
	v_lshrrev_b32_e32 v223, 5, v184
	v_lshl_add_u32 v222, v223, 4, v222
	v_add_u32_e32 v222, 0x1200, v222
	v_mov_b32_e32 v223, s98
	v_lshlrev_b32_e32 v223, 14, v223
	v_add_u32_e32 v223, 0x1680, v223
	global_load_dwordx4 v[198:201], v222, s[50:51]
	global_load_dwordx4 v[244:247], v222, s[50:51] offset:32
	global_load_dwordx4 v[160:163], v222, s[50:51] offset:64
	global_load_dwordx4 v[176:179], v222, s[50:51] offset:96
	global_load_dwordx4 v[224:227], v223, s[50:51]
	v_add_u32_e32 v223, 0x4000, v223
	global_load_dwordx4 v[228:231], v223, s[50:51]
	v_add_u32_e32 v223, 0x4000, v223
	global_load_dwordx4 v[232:235], v223, s[50:51]
	v_add_u32_e32 v223, 0x4000, v223
	global_load_dwordx4 v[236:239], v223, s[50:51]

.LBB0_412:
	s_or_b64 exec, exec, s[0:1]
	s_lshl_b32 s0, s36, 2
	s_sub_i32 s38, 0x200c, s0
	s_sub_i32 s80, 0x210c, s0
	s_cmpk_gt_u32 s80, 0xff
	s_cselect_b64 s[0:1], -1, 0
	s_lshr_b32 s81, s80, 8
	v_mov_b32_e32 v172, v184
	s_cmpk_lt_u32 s80, 0x100
	s_cbranch_scc1 .LBB0_439
	v_readlane_b32 s36, v250, 46
	s_ashr_i32 s39, s38, 31
	v_ashrrev_i32_e32 v0, 5, v172
	v_lshlrev_b32_e32 v168, 3, v172
	v_readlane_b32 s37, v250, 47
	s_lshl_b64 s[48:49], s[38:39], 14
	v_ashrrev_i32_e32 v1, 31, v0
	v_lshl_add_u64 v[96:97], v[168:169], 1, s[36:37]
	s_add_u32 s36, s50, s48
	s_addc_u32 s37, s51, s49
	v_lshlrev_b64 v[2:3], 1, v[0:1]
	v_lshl_add_u64 v[4:5], s[36:37], 0, v[2:3]
	s_or_b32 s36, s38, 1
	s_ashr_i32 s37, s36, 31
	s_lshl_b64 s[44:45], s[36:37], 14
	s_add_u32 s36, s50, s44
	s_addc_u32 s37, s51, s45
	v_lshl_add_u64 v[6:7], s[36:37], 0, v[2:3]
	s_or_b32 s36, s38, 2
	s_ashr_i32 s37, s36, 31
	s_lshl_b64 s[46:47], s[36:37], 14
	s_add_u32 s36, s50, s46
	s_addc_u32 s37, s51, s47
	v_lshl_add_u64 v[8:9], s[36:37], 0, v[2:3]
	s_or_b32 s36, s38, 3
	s_ashr_i32 s37, s36, 31
	s_lshl_b64 s[42:43], s[36:37], 14
	s_movk_i32 s15, 0x1000
	s_add_u32 s36, s50, s42
	v_add_co_u32_e32 v6, vcc, s15, v6
	s_addc_u32 s37, s51, s43
	s_nop 0
	v_addc_co_u32_e32 v7, vcc, 0, v7, vcc
	v_lshl_add_u64 v[10:11], s[36:37], 0, v[2:3]
	v_add_co_u32_e32 v10, vcc, s15, v10
	v_readlane_b32 s39, v250, 54
	s_nop 0
	v_addc_co_u32_e32 v11, vcc, 0, v11, vcc
	s_add_u32 s36, s39, s48
	v_readlane_b32 s58, v250, 55
	s_addc_u32 s37, s58, s49
	v_add_co_u32_e32 v4, vcc, s15, v4
	v_lshl_add_u64 v[12:13], s[36:37], 0, v[2:3]
	s_nop 0
	v_addc_co_u32_e32 v5, vcc, 0, v5, vcc
	s_add_u32 s36, s39, s44
	v_add_co_u32_e32 v12, vcc, s15, v12
	s_addc_u32 s37, s58, s45
	s_nop 0
	v_addc_co_u32_e32 v13, vcc, 0, v13, vcc
	v_lshl_add_u64 v[14:15], s[36:37], 0, v[2:3]
	v_add_co_u32_e32 v14, vcc, s15, v14
	s_add_u32 s36, s39, s46
	s_nop 0
	v_addc_co_u32_e32 v15, vcc, 0, v15, vcc
	s_addc_u32 s37, s58, s47
	v_add_co_u32_e32 v8, vcc, s15, v8
	v_lshl_add_u64 v[16:17], s[36:37], 0, v[2:3]
	s_nop 0
	v_addc_co_u32_e32 v9, vcc, 0, v9, vcc
	s_add_u32 s36, s39, s42
	v_add_co_u32_e32 v16, vcc, s15, v16
	s_addc_u32 s37, s58, s43
	v_readlane_b32 s39, v250, 56
	v_addc_co_u32_e32 v17, vcc, 0, v17, vcc
	v_lshl_add_u64 v[18:19], s[36:37], 0, v[2:3]
	s_add_u32 s36, s39, s48
	v_readlane_b32 s58, v250, 57
	v_add_co_u32_e32 v18, vcc, s15, v18
	s_addc_u32 s37, s58, s49
	s_nop 0
	v_addc_co_u32_e32 v19, vcc, 0, v19, vcc
	v_lshl_add_u64 v[4:5], s[36:37], 0, v[2:3]
	s_add_u32 s36, s39, s44
	s_addc_u32 s37, s58, s45
	v_lshl_add_u64 v[6:7], s[36:37], 0, v[2:3]
	s_add_u32 s36, s39, s46
	s_addc_u32 s37, s58, s47
	v_lshl_add_u64 v[8:9], s[36:37], 0, v[2:3]
	s_add_u32 s36, s39, s42
	v_add_co_u32_e32 v6, vcc, s15, v6
	s_addc_u32 s37, s58, s43
	s_nop 0
	v_addc_co_u32_e32 v7, vcc, 0, v7, vcc
	v_lshl_add_u64 v[10:11], s[36:37], 0, v[2:3]
	v_add_co_u32_e32 v10, vcc, s15, v10
	v_readlane_b32 s39, v250, 58
	s_nop 0
	v_addc_co_u32_e32 v11, vcc, 0, v11, vcc
	s_add_u32 s36, s39, s48
	v_readlane_b32 s48, v250, 59
	s_addc_u32 s37, s48, s49
	v_add_co_u32_e32 v4, vcc, s15, v4
	v_lshl_add_u64 v[12:13], s[36:37], 0, v[2:3]
	s_nop 0
	v_addc_co_u32_e32 v5, vcc, 0, v5, vcc
	s_add_u32 s36, s39, s44
	v_add_co_u32_e32 v12, vcc, s15, v12
	s_addc_u32 s37, s48, s45
	s_nop 0
	v_addc_co_u32_e32 v13, vcc, 0, v13, vcc
	v_lshl_add_u64 v[14:15], s[36:37], 0, v[2:3]
	v_add_co_u32_e32 v14, vcc, s15, v14
	s_add_u32 s36, s39, s46
	s_nop 0
	v_addc_co_u32_e32 v15, vcc, 0, v15, vcc
	s_addc_u32 s37, s48, s47
	v_add_co_u32_e32 v8, vcc, s15, v8
	v_lshl_add_u64 v[16:17], s[36:37], 0, v[2:3]
	s_nop 0
	v_addc_co_u32_e32 v9, vcc, 0, v9, vcc
	s_add_u32 s36, s39, s42
	v_add_co_u32_e32 v16, vcc, s15, v16
	s_addc_u32 s37, s48, s43
	s_nop 0
	v_addc_co_u32_e32 v17, vcc, 0, v17, vcc
	v_lshl_add_u64 v[2:3], s[36:37], 0, v[2:3]
	v_add_co_u32_e32 v2, vcc, s15, v2
	v_and_or_b32 v168, v172, 3, s38
	s_nop 0
	v_addc_co_u32_e32 v3, vcc, 0, v3, vcc
	v_lshlrev_b64 v[2:3], 14, v[168:169]
	v_lshlrev_b32_e32 v4, 5, v172
	s_add_i32 s39, s81, 0x7ffffff
	v_lshl_add_u64 v[2:3], s[50:51], 0, v[2:3]
	v_and_b32_e32 v168, 0x380, v4
	v_lshlrev_b32_e32 v4, 3, v0
	v_lshl_add_u64 v[2:3], v[2:3], 0, v[168:169]
	v_ashrrev_i32_e32 v5, 31, v4
	s_lshl_b32 s44, s39, 5
	v_lshl_add_u64 v[2:3], v[4:5], 1, v[2:3]
	s_mov_b64 s[36:37], 0x1200
	s_cmpk_lt_u32 s80, 0x300
	v_lshl_add_u64 v[4:5], v[2:3], 0, s[36:37]
	s_cselect_b32 s36, s44, 64
	s_add_i32 s36, s36, s76
	s_or_b32 s42, s36, 3
	v_add_co_u32_e32 v2, vcc, s15, v2
	s_ashr_i32 s43, s42, 31
	s_nop 0
	v_addc_co_u32_e32 v3, vcc, 0, v3, vcc
	s_lshl_b64 s[42:43], s[42:43], 10
	v_lshl_add_u64 v[2:3], v[96:97], 0, s[42:43]
	s_or_b32 s42, s36, 2
	s_ashr_i32 s43, s42, 31
	s_lshl_b64 s[42:43], s[42:43], 10
	v_lshl_add_u64 v[4:5], v[96:97], 0, s[42:43]
	s_or_b32 s42, s36, 1
	s_ashr_i32 s43, s42, 31
	s_ashr_i32 s37, s36, 31
	s_lshl_b64 s[42:43], s[42:43], 10
	s_lshl_b64 s[36:37], s[36:37], 10
	s_cmpk_lt_u32 s80, 0x200
	global_load_dwordx4 v[48:51], v[2:3], off
	global_load_dwordx4 v[52:55], v[4:5], off
	v_lshl_add_u64 v[4:5], v[96:97], 0, s[36:37]
	s_cselect_b32 s36, s44, 32
	s_add_i32 s36, s36, s76
	v_lshl_add_u64 v[2:3], v[96:97], 0, s[42:43]
	s_or_b32 s42, s36, 3
	s_ashr_i32 s43, s42, 31
	s_lshl_b64 s[42:43], s[42:43], 10
	global_load_dwordx4 v[56:59], v[2:3], off
	global_load_dwordx4 v[60:63], v[4:5], off
	v_lshl_add_u64 v[2:3], v[96:97], 0, s[42:43]
	s_or_b32 s42, s36, 2
	s_ashr_i32 s43, s42, 31
	s_lshl_b64 s[42:43], s[42:43], 10
	v_lshl_add_u64 v[4:5], v[96:97], 0, s[42:43]
	s_or_b32 s42, s36, 1
	s_ashr_i32 s37, s36, 31
	s_ashr_i32 s43, s42, 31
	s_lshl_b64 s[36:37], s[36:37], 10
	s_lshl_b64 s[42:43], s[42:43], 10
	v_lshl_add_u64 v[4:5], v[96:97], 0, s[36:37]
	v_readlane_b32 s36, v251, 50
	v_lshl_add_u64 v[2:3], v[96:97], 0, s[42:43]
	v_readlane_b32 s37, v251, 51
	v_lshl_add_u64 v[2:3], v[96:97], 0, s[36:37]
	v_lshl_add_u64 v[4:5], v[96:97], 0, s[6:7]
	v_lshl_add_u64 v[2:3], v[96:97], 0, s[10:11]
	v_lshl_add_u64 v[4:5], v[96:97], 0, s[12:13]
	v_lshrrev_b32_e32 v240, 5, v172
	v_sub_u32_e32 v240, 1, v240
	v_lshlrev_b32_e32 v240, 4, v240
	s_waitcnt vmcnt(4)
	v_lshlrev_b32_e32 v242, v240, v224
	v_and_b32_e32 v98, 0xffff0000, v242
	v_lshlrev_b32_e32 v242, v240, v228
	v_and_b32_e32 v106, 0xffff0000, v242
	v_lshlrev_b32_e32 v242, v240, v232
	v_and_b32_e32 v100, 0xffff0000, v242
	v_lshlrev_b32_e32 v242, v240, v236
	v_and_b32_e32 v107, 0xffff0000, v242
	v_lshlrev_b32_e32 v242, v240, v225
	v_and_b32_e32 v99, 0xffff0000, v242
	v_lshlrev_b32_e32 v242, v240, v229
	v_and_b32_e32 v108, 0xffff0000, v242
	v_lshlrev_b32_e32 v242, v240, v233
	v_and_b32_e32 v101, 0xffff0000, v242
	v_lshlrev_b32_e32 v242, v240, v237
	v_and_b32_e32 v109, 0xffff0000, v242
	v_lshlrev_b32_e32 v242, v240, v226
	v_and_b32_e32 v102, 0xffff0000, v242
	v_lshlrev_b32_e32 v242, v240, v230
	v_and_b32_e32 v110, 0xffff0000, v242
	v_lshlrev_b32_e32 v242, v240, v234
	v_and_b32_e32 v104, 0xffff0000, v242
	v_lshlrev_b32_e32 v242, v240, v238
	v_and_b32_e32 v111, 0xffff0000, v242
	v_lshlrev_b32_e32 v242, v240, v227
	v_and_b32_e32 v103, 0xffff0000, v242
	v_lshlrev_b32_e32 v242, v240, v231
	v_and_b32_e32 v112, 0xffff0000, v242
	v_lshlrev_b32_e32 v242, v240, v235
	v_and_b32_e32 v105, 0xffff0000, v242
	v_lshlrev_b32_e32 v242, v240, v239
	v_and_b32_e32 v113, 0xffff0000, v242
	v_lshlrev_b32_e32 v1, 1, v0
	s_mov_b32 s36, 0x10800
	v_and_b32_e32 v2, 31, v172
	v_mul_lo_u32 v3, v0, s36
	v_lshl_add_u32 v115, v0, 13, s17
	v_or_b32_e32 v0, 1, v1
	v_add_u32_e32 v116, s38, v0
	v_lshl_add_u32 v117, v0, 12, s17
	v_lshl_or_b32 v0, v2, 2, v3
	v_add_u32_e32 v114, s38, v1
	v_add_u32_e32 v118, s4, v2
	v_add_u32_e32 v119, s14, v0
	s_waitcnt vmcnt(4)
	v_mov_b32_e32 v36, v80
	v_mov_b32_e32 v37, v81
	v_mov_b32_e32 v38, v82
	v_mov_b32_e32 v39, v83
	v_mov_b32_e32 v32, v84
	v_mov_b32_e32 v33, v85
	v_mov_b32_e32 v34, v86
	v_mov_b32_e32 v35, v87
	v_mov_b32_e32 v44, v88
	v_mov_b32_e32 v45, v89
	v_mov_b32_e32 v46, v90
	v_mov_b32_e32 v47, v91
	v_mov_b32_e32 v40, v92
	v_mov_b32_e32 v41, v93
	v_mov_b32_e32 v42, v94
	v_mov_b32_e32 v43, v95
	v_mov_b32_e32 v76, v206
	v_mov_b32_e32 v77, v207
	v_mov_b32_e32 v78, v208
	v_mov_b32_e32 v79, v209
	v_mov_b32_e32 v72, v210
	v_mov_b32_e32 v73, v211
	v_mov_b32_e32 v74, v212
	v_mov_b32_e32 v75, v213
	v_mov_b32_e32 v68, v214
	v_mov_b32_e32 v69, v215
	v_mov_b32_e32 v70, v216
	v_mov_b32_e32 v71, v217
	v_mov_b32_e32 v64, v218
	v_mov_b32_e32 v65, v219
	v_mov_b32_e32 v66, v220
	v_mov_b32_e32 v67, v221
	v_mov_b32_e32 v28, v198
	v_mov_b32_e32 v29, v199
	v_mov_b32_e32 v30, v200
	v_mov_b32_e32 v31, v201
	v_mov_b32_e32 v20, v244
	v_mov_b32_e32 v21, v245
	v_mov_b32_e32 v22, v246
	v_mov_b32_e32 v23, v247
	v_mov_b32_e32 v16, v160
	v_mov_b32_e32 v17, v161
	v_mov_b32_e32 v18, v162
	v_mov_b32_e32 v19, v163
	v_mov_b32_e32 v24, v176
	v_mov_b32_e32 v25, v177
	v_mov_b32_e32 v26, v178
	v_mov_b32_e32 v27, v179
	s_mov_b32 s46, 6
	s_branch .LBB0_416

.LBB0_513:
	s_or_b64 exec, exec, s[0:1]
	v_readlane_b32 s98, v250, 46
	v_readlane_b32 s99, v250, 47
	v_and_b32_e32 v222, 63, v171
	v_lshrrev_b32_e32 v223, 6, v171
	v_lshlrev_b32_e32 v222, 4, v222
	v_lshl_add_u32 v222, v223, 12, v222
	s_nop 1
	global_load_dwordx4 v[80:83], v222, s[98:99]
	global_load_dwordx4 v[84:87], v222, s[98:99] offset:1024
	global_load_dwordx4 v[88:91], v222, s[98:99] offset:2048
	global_load_dwordx4 v[92:95], v222, s[98:99] offset:3072
	s_add_u32 s98, s98, 0x8000
	s_addc_u32 s99, s99, 0
	global_load_dwordx4 v[206:209], v222, s[98:99]
	global_load_dwordx4 v[210:213], v222, s[98:99] offset:1024
	global_load_dwordx4 v[214:217], v222, s[98:99] offset:2048
	global_load_dwordx4 v[218:221], v222, s[98:99] offset:3072
	s_mov_b64 s[0:1], exec
	v_readlane_b32 s36, v250, 52
	v_readlane_b32 s37, v250, 53
	s_and_b64 s[36:37], s[0:1], s[36:37]
	s_mov_b64 exec, s[36:37]
	s_cbranch_execz .LBB0_515
	v_lshl_add_u32 v64, v172, 2, v193
	ds_write2st64_b32 v64, v204, v164 offset1:1
	ds_write2st64_b32 v64, v60, v61 offset0:2 offset1:3
	ds_write2st64_b32 v64, v62, v63 offset0:4 offset1:5
	ds_write2st64_b32 v64, v56, v57 offset0:6 offset1:7
	ds_write2st64_b32 v64, v58, v59 offset0:8 offset1:9
	ds_write2st64_b32 v64, v52, v53 offset0:10 offset1:11
	ds_write2st64_b32 v64, v54, v55 offset0:12 offset1:13
	ds_write2st64_b32 v64, v48, v49 offset0:14 offset1:15
	ds_write2st64_b32 v64, v50, v51 offset0:16 offset1:17
	ds_write2st64_b32 v64, v44, v45 offset0:18 offset1:19
	ds_write2st64_b32 v64, v46, v47 offset0:20 offset1:21
	ds_write2st64_b32 v64, v40, v41 offset0:22 offset1:23
	ds_write2st64_b32 v64, v42, v43 offset0:24 offset1:25
	ds_write2st64_b32 v64, v36, v37 offset0:26 offset1:27
	ds_write2st64_b32 v64, v38, v39 offset0:28 offset1:29
	ds_write2st64_b32 v64, v32, v33 offset0:30 offset1:31
	ds_write2st64_b32 v64, v34, v35 offset0:32 offset1:33
	ds_write2st64_b32 v64, v28, v29 offset0:34 offset1:35
	ds_write2st64_b32 v64, v30, v31 offset0:36 offset1:37
	ds_write2st64_b32 v64, v24, v25 offset0:38 offset1:39
	ds_write2st64_b32 v64, v26, v27 offset0:40 offset1:41
	ds_write2st64_b32 v64, v20, v21 offset0:42 offset1:43
	ds_write2st64_b32 v64, v22, v23 offset0:44 offset1:45
	ds_write2st64_b32 v64, v16, v17 offset0:46 offset1:47
	ds_write2st64_b32 v64, v18, v19 offset0:48 offset1:49
	ds_write2st64_b32 v64, v12, v13 offset0:50 offset1:51
	ds_write2st64_b32 v64, v14, v15 offset0:52 offset1:53
	ds_write2st64_b32 v64, v8, v9 offset0:54 offset1:55
	ds_write2st64_b32 v64, v10, v11 offset0:56 offset1:57
	ds_write2st64_b32 v64, v4, v5 offset0:58 offset1:59
	ds_write2st64_b32 v64, v6, v7 offset0:60 offset1:61
	ds_write2st64_b32 v64, v0, v1 offset0:62 offset1:63
	ds_write2st64_b32 v64, v2, v3 offset0:64 offset1:65
.LBB0_515:
	s_or_b64 exec, exec, s[0:1]
	s_and_saveexec_b64 s[98:99], s[8:9]
	s_cbranch_execz .Lkq_nw
	s_waitcnt vmcnt(8)
	v_mov_b32_e32 v222, s86
	ds_write_b32 v222, v196
.Lkq_nw:
	s_or_b64 exec, exec, s[98:99]
	s_waitcnt lgkmcnt(0)
	s_barrier
	v_mov_b32_e32 v222, s86
	ds_read_b32 v223, v222
	s_waitcnt lgkmcnt(0)
	v_readfirstlane_b32 s98, v223
	s_cmpk_lt_i32 s98, 0x804
	s_cbranch_scc0 .Lkq_skip_b
	s_lshl_b32 s98, s98, 2
	s_sub_i32 s98, 0x200c, s98
	v_and_b32_e32 v222, 3, v184
	v_or_b32_e32 v222, s98, v222
	v_lshlrev_b32_e32 v222, 14, v222
	v_lshlrev_b32_e32 v223, 5, v184
	v_and_b32_e32 v223, 0x380, v223
	v_add_u32_e32 v222, v222, v223
	v_lshrrev_b32_e32 v223, 5, v184
	v_lshl_add_u32 v222, v223, 4, v222
	v_add_u32_e32 v222, 0x1200, v222
	v_mov_b32_e32 v223, s98
	v_lshlrev_b32_e32 v223, 14, v223
	v_add_u32_e32 v223, 0x1680, v223
	global_load_dwordx4 v[198:201], v222, s[50:51]
	global_load_dwordx4 v[244:247], v222, s[50:51] offset:32
	global_load_dwordx4 v[160:163], v222, s[50:51] offset:64
	global_load_dwordx4 v[176:179], v222, s[50:51] offset:96
	global_load_dwordx4 v[224:227], v223, s[50:51]
	v_add_u32_e32 v223, 0x4000, v223
	global_load_dwordx4 v[228:231], v223, s[50:51]
	v_add_u32_e32 v223, 0x4000, v223
	global_load_dwordx4 v[232:235], v223, s[50:51]
	v_add_u32_e32 v223, 0x4000, v223
	global_load_dwordx4 v[236:239], v223, s[50:51]
.Lkq_skip_b:
	s_and_saveexec_b64 s[0:1], s[40:41]
	s_cbranch_execz .LBB0_517
	s_waitcnt vmcnt(16)
	v_lshl_add_u32 v67, v172, 2, v194
	ds_read2st64_b32 v[68:69], v67 offset1:1
	ds_read2st64_b32 v[96:97], v67 offset0:2 offset1:3
	ds_read2st64_b32 v[98:99], v67 offset0:4 offset1:5
	ds_read2st64_b32 v[100:101], v67 offset0:6 offset1:7
	ds_read2st64_b32 v[102:103], v67 offset0:8 offset1:9
	ds_read2st64_b32 v[104:105], v67 offset0:10 offset1:11
	ds_read2st64_b32 v[106:107], v67 offset0:12 offset1:13
	ds_read2st64_b32 v[108:109], v67 offset0:14 offset1:15
	ds_read2st64_b32 v[110:111], v67 offset0:16 offset1:17
	ds_read2st64_b32 v[112:113], v67 offset0:18 offset1:19
	ds_read2st64_b32 v[114:115], v67 offset0:20 offset1:21
	ds_read2st64_b32 v[116:117], v67 offset0:22 offset1:23
	ds_read2st64_b32 v[118:119], v67 offset0:24 offset1:25
	ds_read2st64_b32 v[120:121], v67 offset0:26 offset1:27
	ds_read2st64_b32 v[122:123], v67 offset0:28 offset1:29
	ds_read2st64_b32 v[124:125], v67 offset0:30 offset1:31
	ds_read2st64_b32 v[126:127], v67 offset0:32 offset1:33
	ds_read2st64_b32 v[128:129], v67 offset0:34 offset1:35
	ds_read2st64_b32 v[130:131], v67 offset0:36 offset1:37
	ds_read2st64_b32 v[132:133], v67 offset0:38 offset1:39
	ds_read2st64_b32 v[134:135], v67 offset0:40 offset1:41
	ds_read2st64_b32 v[136:137], v67 offset0:42 offset1:43
	ds_read2st64_b32 v[138:139], v67 offset0:44 offset1:45
	ds_read2st64_b32 v[140:141], v67 offset0:46 offset1:47
	ds_read2st64_b32 v[142:143], v67 offset0:48 offset1:49
	ds_read2st64_b32 v[144:145], v67 offset0:50 offset1:51
	ds_read2st64_b32 v[146:147], v67 offset0:52 offset1:53
	ds_read2st64_b32 v[148:149], v67 offset0:54 offset1:55
	ds_read2st64_b32 v[150:151], v67 offset0:56 offset1:57
	ds_read2st64_b32 v[152:153], v67 offset0:58 offset1:59
	ds_read2st64_b32 v[154:155], v67 offset0:60 offset1:61
	ds_read2st64_b32 v[156:157], v67 offset0:62 offset1:63
	ds_read2st64_b32 v[158:159], v67 offset0:64 offset1:65
	v_max_f32_e32 v70, v204, v204
	v_readlane_b32 s36, v250, 50
	v_readlane_b32 s37, v250, 51
	v_and_b32_e32 v75, 15, v172
	v_lshrrev_b32_e32 v76, 4, v172
	v_mul_u32_u24_e32 v75, 0x210, v75
	v_lshl_add_u32 v75, v76, 3, v75
	v_add_u32_e32 v75, v75, v193
	v_lshrrev_b32_e32 v76, 5, v172
	v_mul_u32_u24_e32 v76, 0x210, v76
	v_and_b32_e32 v77, 31, v172
	v_lshl_add_u32 v76, v77, 4, v76
	v_add_u32_e32 v76, v76, v193
	s_waitcnt lgkmcnt(0)
	v_max_f32_e32 v66, v68, v68
	v_max_f32_e32 v66, v70, v66
	v_sub_f32_e32 v70, v204, v66
	v_sub_f32_e32 v66, v68, v66
	v_exp_f32_e32 v70, v70
	v_exp_f32_e32 v71, v66
	v_mov_b32_e32 v165, v69
	v_lshl_add_u64 v[64:65], v[174:175], 1, s[36:37]
	v_lshlrev_b32_e32 v72, 4, v172
	v_mov_b32_e32 v73, 0
	v_pk_mul_f32 v[68:69], v[164:165], v[70:71]
	v_lshl_add_u64 v[64:65], v[64:65], 0, v[72:73]
	v_add_f32_e32 v66, v68, v69
	v_div_scale_f32 v68, s[36:37], v66, v66, 1.0
	v_rcp_f32_e32 v69, v68
	s_nop 0
	v_fma_f32 v72, -v68, v69, 1.0
	v_fmac_f32_e32 v69, v72, v69
	v_div_scale_f32 v72, vcc, 1.0, v66, 1.0
	v_mul_f32_e32 v73, v72, v69
	v_fma_f32 v74, -v68, v73, v72
	v_fmac_f32_e32 v73, v74, v69
	v_fma_f32 v68, -v68, v73, v72
	v_div_fmas_f32 v68, v68, v69, v73
	v_div_fixup_f32 v68, v68, v66, 1.0
	v_mul_f32_e32 v66, v70, v68
	v_mul_f32_e32 v68, v71, v68
	s_mov_b64 s[36:37], 0x1000
	v_lshl_add_u64 v[78:79], v[64:65], 0, s[36:37]
	v_pk_mul_f32 v[96:97], v[68:69], v[96:97] op_sel_hi:[0,1]
	v_pk_mul_f32 v[98:99], v[68:69], v[98:99] op_sel_hi:[0,1]
	v_pk_fma_f32 v[60:61], v[66:67], v[60:61], v[96:97] op_sel_hi:[0,1,1]
	v_pk_fma_f32 v[62:63], v[66:67], v[62:63], v[98:99] op_sel_hi:[0,1,1]
	v_cvt_pk_bf16_f32 v60, v60, v61
	v_cvt_pk_bf16_f32 v61, v62, v63
	ds_write_b64 v75, v[60:61]
	v_pk_mul_f32 v[100:101], v[68:69], v[100:101] op_sel_hi:[0,1]
	v_pk_mul_f32 v[102:103], v[68:69], v[102:103] op_sel_hi:[0,1]
	v_pk_fma_f32 v[56:57], v[66:67], v[56:57], v[100:101] op_sel_hi:[0,1,1]
	v_pk_fma_f32 v[58:59], v[66:67], v[58:59], v[102:103] op_sel_hi:[0,1,1]
	v_cvt_pk_bf16_f32 v56, v56, v57
	v_cvt_pk_bf16_f32 v57, v58, v59
	ds_write_b64 v75, v[56:57] offset:32
	v_pk_mul_f32 v[104:105], v[68:69], v[104:105] op_sel_hi:[0,1]
	v_pk_mul_f32 v[106:107], v[68:69], v[106:107] op_sel_hi:[0,1]
	v_pk_fma_f32 v[52:53], v[66:67], v[52:53], v[104:105] op_sel_hi:[0,1,1]
	v_pk_fma_f32 v[54:55], v[66:67], v[54:55], v[106:107] op_sel_hi:[0,1,1]
	v_cvt_pk_bf16_f32 v52, v52, v53
	v_cvt_pk_bf16_f32 v53, v54, v55
	ds_write_b64 v75, v[52:53] offset:64
	v_pk_mul_f32 v[108:109], v[68:69], v[108:109] op_sel_hi:[0,1]
	v_pk_mul_f32 v[110:111], v[68:69], v[110:111] op_sel_hi:[0,1]
	v_pk_fma_f32 v[48:49], v[66:67], v[48:49], v[108:109] op_sel_hi:[0,1,1]
	v_pk_fma_f32 v[50:51], v[66:67], v[50:51], v[110:111] op_sel_hi:[0,1,1]
	v_cvt_pk_bf16_f32 v48, v48, v49
	v_cvt_pk_bf16_f32 v49, v50, v51
	ds_write_b64 v75, v[48:49] offset:96
	v_pk_mul_f32 v[112:113], v[68:69], v[112:113] op_sel_hi:[0,1]
	v_pk_mul_f32 v[114:115], v[68:69], v[114:115] op_sel_hi:[0,1]
	v_pk_fma_f32 v[44:45], v[66:67], v[44:45], v[112:113] op_sel_hi:[0,1,1]
	v_pk_fma_f32 v[46:47], v[66:67], v[46:47], v[114:115] op_sel_hi:[0,1,1]
	v_cvt_pk_bf16_f32 v44, v44, v45
	v_cvt_pk_bf16_f32 v45, v46, v47
	ds_write_b64 v75, v[44:45] offset:128
	v_pk_mul_f32 v[116:117], v[68:69], v[116:117] op_sel_hi:[0,1]
	v_pk_mul_f32 v[118:119], v[68:69], v[118:119] op_sel_hi:[0,1]
	v_pk_fma_f32 v[40:41], v[66:67], v[40:41], v[116:117] op_sel_hi:[0,1,1]
	v_pk_fma_f32 v[42:43], v[66:67], v[42:43], v[118:119] op_sel_hi:[0,1,1]
	v_cvt_pk_bf16_f32 v40, v40, v41
	v_cvt_pk_bf16_f32 v41, v42, v43
	ds_write_b64 v75, v[40:41] offset:160
	v_pk_mul_f32 v[120:121], v[68:69], v[120:121] op_sel_hi:[0,1]
	v_pk_mul_f32 v[122:123], v[68:69], v[122:123] op_sel_hi:[0,1]
	v_pk_fma_f32 v[36:37], v[66:67], v[36:37], v[120:121] op_sel_hi:[0,1,1]
	v_pk_fma_f32 v[38:39], v[66:67], v[38:39], v[122:123] op_sel_hi:[0,1,1]
	v_cvt_pk_bf16_f32 v36, v36, v37
	v_cvt_pk_bf16_f32 v37, v38, v39
	ds_write_b64 v75, v[36:37] offset:192
	v_pk_mul_f32 v[124:125], v[68:69], v[124:125] op_sel_hi:[0,1]
	v_pk_mul_f32 v[126:127], v[68:69], v[126:127] op_sel_hi:[0,1]
	v_pk_fma_f32 v[32:33], v[66:67], v[32:33], v[124:125] op_sel_hi:[0,1,1]
	v_pk_fma_f32 v[34:35], v[66:67], v[34:35], v[126:127] op_sel_hi:[0,1,1]
	v_cvt_pk_bf16_f32 v32, v32, v33
	v_cvt_pk_bf16_f32 v33, v34, v35
	ds_write_b64 v75, v[32:33] offset:224
	v_pk_mul_f32 v[128:129], v[68:69], v[128:129] op_sel_hi:[0,1]
	v_pk_mul_f32 v[130:131], v[68:69], v[130:131] op_sel_hi:[0,1]
	v_pk_fma_f32 v[28:29], v[66:67], v[28:29], v[128:129] op_sel_hi:[0,1,1]
	v_pk_fma_f32 v[30:31], v[66:67], v[30:31], v[130:131] op_sel_hi:[0,1,1]
	v_cvt_pk_bf16_f32 v28, v28, v29
	v_cvt_pk_bf16_f32 v29, v30, v31
	ds_write_b64 v75, v[28:29] offset:256
	v_pk_mul_f32 v[132:133], v[68:69], v[132:133] op_sel_hi:[0,1]
	v_pk_mul_f32 v[134:135], v[68:69], v[134:135] op_sel_hi:[0,1]
	v_pk_fma_f32 v[24:25], v[66:67], v[24:25], v[132:133] op_sel_hi:[0,1,1]
	v_pk_fma_f32 v[26:27], v[66:67], v[26:27], v[134:135] op_sel_hi:[0,1,1]
	v_cvt_pk_bf16_f32 v24, v24, v25
	v_cvt_pk_bf16_f32 v25, v26, v27
	ds_write_b64 v75, v[24:25] offset:288
	v_pk_mul_f32 v[136:137], v[68:69], v[136:137] op_sel_hi:[0,1]
	v_pk_mul_f32 v[138:139], v[68:69], v[138:139] op_sel_hi:[0,1]
	v_pk_fma_f32 v[20:21], v[66:67], v[20:21], v[136:137] op_sel_hi:[0,1,1]
	v_pk_fma_f32 v[22:23], v[66:67], v[22:23], v[138:139] op_sel_hi:[0,1,1]
	v_cvt_pk_bf16_f32 v20, v20, v21
	v_cvt_pk_bf16_f32 v21, v22, v23
	ds_write_b64 v75, v[20:21] offset:320
	v_pk_mul_f32 v[140:141], v[68:69], v[140:141] op_sel_hi:[0,1]
	v_pk_mul_f32 v[142:143], v[68:69], v[142:143] op_sel_hi:[0,1]
	v_pk_fma_f32 v[16:17], v[66:67], v[16:17], v[140:141] op_sel_hi:[0,1,1]
	v_pk_fma_f32 v[18:19], v[66:67], v[18:19], v[142:143] op_sel_hi:[0,1,1]
	v_cvt_pk_bf16_f32 v16, v16, v17
	v_cvt_pk_bf16_f32 v17, v18, v19
	ds_write_b64 v75, v[16:17] offset:352
	v_pk_mul_f32 v[144:145], v[68:69], v[144:145] op_sel_hi:[0,1]
	v_pk_mul_f32 v[146:147], v[68:69], v[146:147] op_sel_hi:[0,1]
	v_pk_fma_f32 v[12:13], v[66:67], v[12:13], v[144:145] op_sel_hi:[0,1,1]
	v_pk_fma_f32 v[14:15], v[66:67], v[14:15], v[146:147] op_sel_hi:[0,1,1]
	v_cvt_pk_bf16_f32 v12, v12, v13
	v_cvt_pk_bf16_f32 v13, v14, v15
	ds_write_b64 v75, v[12:13] offset:384
	v_pk_mul_f32 v[148:149], v[68:69], v[148:149] op_sel_hi:[0,1]
	v_pk_mul_f32 v[150:151], v[68:69], v[150:151] op_sel_hi:[0,1]
	v_pk_fma_f32 v[8:9], v[66:67], v[8:9], v[148:149] op_sel_hi:[0,1,1]
	v_pk_fma_f32 v[10:11], v[66:67], v[10:11], v[150:151] op_sel_hi:[0,1,1]
	v_cvt_pk_bf16_f32 v8, v8, v9
	v_cvt_pk_bf16_f32 v9, v10, v11
	ds_write_b64 v75, v[8:9] offset:416
	v_pk_mul_f32 v[152:153], v[68:69], v[152:153] op_sel_hi:[0,1]
	v_pk_mul_f32 v[154:155], v[68:69], v[154:155] op_sel_hi:[0,1]
	v_pk_fma_f32 v[4:5], v[66:67], v[4:5], v[152:153] op_sel_hi:[0,1,1]
	v_pk_fma_f32 v[6:7], v[66:67], v[6:7], v[154:155] op_sel_hi:[0,1,1]
	v_cvt_pk_bf16_f32 v4, v4, v5
	v_cvt_pk_bf16_f32 v5, v6, v7
	ds_write_b64 v75, v[4:5] offset:448
	v_pk_mul_f32 v[156:157], v[68:69], v[156:157] op_sel_hi:[0,1]
	v_pk_mul_f32 v[158:159], v[68:69], v[158:159] op_sel_hi:[0,1]
	v_pk_fma_f32 v[0:1], v[66:67], v[0:1], v[156:157] op_sel_hi:[0,1,1]
	v_pk_fma_f32 v[2:3], v[66:67], v[2:3], v[158:159] op_sel_hi:[0,1,1]
	v_cvt_pk_bf16_f32 v0, v0, v1
	v_cvt_pk_bf16_f32 v1, v2, v3
	ds_write_b64 v75, v[0:1] offset:480
	s_waitcnt lgkmcnt(0)
	ds_read_b128 v[96:99], v76
	ds_read_b128 v[100:103], v76 offset:1056
	ds_read_b128 v[104:107], v76 offset:2112
	ds_read_b128 v[108:111], v76 offset:3168
	ds_read_b128 v[112:115], v76 offset:4224
	ds_read_b128 v[116:119], v76 offset:5280
	ds_read_b128 v[120:123], v76 offset:6336
	ds_read_b128 v[124:127], v76 offset:7392
	s_waitcnt lgkmcnt(7)
	global_store_dwordx4 v[64:65], v[96:99], off
	s_waitcnt lgkmcnt(6)
	global_store_dwordx4 v[64:65], v[100:103], off offset:1024
	s_waitcnt lgkmcnt(5)
	global_store_dwordx4 v[64:65], v[104:107], off offset:2048
	s_waitcnt lgkmcnt(4)
	global_store_dwordx4 v[64:65], v[108:111], off offset:3072
	s_waitcnt lgkmcnt(3)
	global_store_dwordx4 v[78:79], v[112:115], off
	s_waitcnt lgkmcnt(2)
	global_store_dwordx4 v[78:79], v[116:119], off offset:1024
	s_waitcnt lgkmcnt(1)
	global_store_dwordx4 v[78:79], v[120:123], off offset:2048
	s_waitcnt lgkmcnt(0)
	global_store_dwordx4 v[78:79], v[124:127], off offset:3072
.LBB0_517:
	s_or_b64 exec, exec, s[0:1]
	v_readlane_b32 s0, v250, 36
	v_readlane_b32 s1, v250, 37
	s_and_b64 s[36:37], s[0:1], s[44:45]
	s_and_saveexec_b64 s[0:1], s[36:37]
	s_cbranch_execz .LBB0_407
	s_cmp_lg_u32 s86, -1
	s_cselect_b32 s36, s86, 0
	s_cselect_b32 s37, s5, 0
	v_mov_b32_e32 v0, s36
	v_mov_b32_e32 v1, s37
	s_waitcnt vmcnt(24)
	ds_write_b32 v0, v196
	s_waitcnt lgkmcnt(0)
	s_branch .LBB0_407
